# v18 + grid barrier: non-leader workgroups poll the cross-XCC generation word directly (one release hop less)
# speedup vs baseline: 1.0015x; 1.0015x over previous
; __device__ __forceinline__ unsigned xb_ld(unsigned* p)              { return __hip_atomic_load(p, __ATOMIC_RELAXED, __HIP_MEMORY_SCOPE_AGENT); }
; __device__ __forceinline__ unsigned xb_add(unsigned* p, unsigned v) { return __hip_atomic_fetch_add(p, v, __ATOMIC_RELAXED, __HIP_MEMORY_SCOPE_AGENT); }
; #define XB_SPIN(cond, bar) do { unsigned _sp = 0; while (cond) { __builtin_amdgcn_s_sleep(1); \
;     if ((++_sp & 255u) == 0u) { if (xb_ld(&(bar)[XB_TMO])) break; if (_sp > XB_SPIN_CAP) { atomicAdd(&(bar)[XB_TMO], 1u); break; } } } } while (0)
; __device__ __forceinline__ void xcd_barrier(const XcdBarrier& b) {
;     ...
;         const unsigned old = xb_add(&bar[XB_XSUB(b.x)], 1u);
;         const unsigned gen = old / nloc;
;         if (old + 1u == (gen + 1u) * nloc) {
;             __builtin_amdgcn_fence(__ATOMIC_RELEASE, "agent");
;             asm volatile("s_waitcnt vmcnt(0)" ::: "memory");
;             const unsigned og = xb_add(&bar[XB_TOP], 1u);
;             const unsigned tg = og / nx;
;             if (og + 1u == (tg + 1u) * nx) xb_add(&bar[XB_TOPGEN], 1u);
;             else XB_SPIN(xb_ld(&bar[XB_TOPGEN]) == tg, bar);
;             __builtin_amdgcn_fence(__ATOMIC_ACQUIRE, "agent");
;             xb_add(&bar[XB_XGEN(b.x)], 1u);
;             asm volatile("s_waitcnt vmcnt(0)" ::: "memory");
;         } else {
;             XB_SPIN(xb_ld(&bar[XB_XGEN(b.x)]) == gen, bar);
.LBB0_497:
	s_or_b64 exec, exec, s[10:11]
	v_cvt_f32_u32_e32 v5, v3
	s_waitcnt vmcnt(0)
	v_readfirstlane_b32 s8, v4
	v_sub_u32_e32 v4, 0, v3
	v_rcp_iflag_f32_e32 v5, v5
	v_add_u32_e32 v6, s8, v0
	v_mul_f32_e32 v5, 0x4f7ffffe, v5
	v_cvt_u32_f32_e32 v5, v5
	v_mul_lo_u32 v0, v4, v5
	v_mul_hi_u32 v0, v5, v0
	v_add_u32_e32 v0, v5, v0
	v_mul_hi_u32 v0, v6, v0
	v_mul_lo_u32 v4, v0, v3
	v_sub_u32_e32 v4, v6, v4
	v_add_u32_e32 v5, 1, v0
	v_cmp_ge_u32_e32 vcc, v4, v3
	s_nop 1
	v_cndmask_b32_e32 v0, v0, v5, vcc
	v_sub_u32_e32 v5, v4, v3
	v_cndmask_b32_e32 v4, v4, v5, vcc
	v_add_u32_e32 v5, 1, v0
	v_cmp_ge_u32_e32 vcc, v4, v3
	v_add_u32_e32 v4, 1, v6
	s_nop 0
	v_cndmask_b32_e32 v0, v0, v5, vcc
	v_mul_lo_u32 v5, v3, v0
	v_add_u32_e32 v3, v5, v3
	v_cmp_ne_u32_e32 vcc, v4, v3
	s_and_saveexec_b64 s[8:9], vcc
	s_xor_b64 s[8:9], exec, s[8:9]
	s_cbranch_execz .LBB0_511
	s_waitcnt lgkmcnt(0)
	v_readlane_b32 s12, v254, 18
	v_readlane_b32 s13, v254, 19
	s_nop 4
	global_load_dword v2, v1, s[12:13] sc1
	s_waitcnt vmcnt(0)
	v_cmp_eq_u32_e32 vcc, v2, v0
	s_and_saveexec_b64 s[10:11], vcc
	s_cbranch_execz .LBB0_510
	s_mov_b32 s24, 1
	s_mov_b64 s[14:15], 0
	s_branch .LBB0_501

; __device__ __forceinline__ unsigned xb_ld(unsigned* p)              { return __hip_atomic_load(p, __ATOMIC_RELAXED, __HIP_MEMORY_SCOPE_AGENT); }
; __device__ __forceinline__ unsigned xb_add(unsigned* p, unsigned v) { return __hip_atomic_fetch_add(p, v, __ATOMIC_RELAXED, __HIP_MEMORY_SCOPE_AGENT); }
; #define XB_SPIN(cond, bar) do { unsigned _sp = 0; while (cond) { __builtin_amdgcn_s_sleep(1); \
;     if ((++_sp & 255u) == 0u) { if (xb_ld(&(bar)[XB_TMO])) break; if (_sp > XB_SPIN_CAP) { atomicAdd(&(bar)[XB_TMO], 1u); break; } } } } while (0)
; __device__ __forceinline__ void xcd_barrier(const XcdBarrier& b) {
;     ...
;         const unsigned old = xb_add(&bar[XB_XSUB(b.x)], 1u);
;         const unsigned gen = old / nloc;
;         if (old + 1u == (gen + 1u) * nloc) {
;             __builtin_amdgcn_fence(__ATOMIC_RELEASE, "agent");
;             asm volatile("s_waitcnt vmcnt(0)" ::: "memory");
;             const unsigned og = xb_add(&bar[XB_TOP], 1u);
;             const unsigned tg = og / nx;
;             if (og + 1u == (tg + 1u) * nx) xb_add(&bar[XB_TOPGEN], 1u);
;             else XB_SPIN(xb_ld(&bar[XB_TOPGEN]) == tg, bar);
;             __builtin_amdgcn_fence(__ATOMIC_ACQUIRE, "agent");
;             xb_add(&bar[XB_XGEN(b.x)], 1u);
;             asm volatile("s_waitcnt vmcnt(0)" ::: "memory");
;         } else {
;             XB_SPIN(xb_ld(&bar[XB_XGEN(b.x)]) == gen, bar);
.LBB0_1194:
	s_or_b64 exec, exec, s[16:17]
	v_cvt_f32_u32_e32 v5, v3
	s_waitcnt vmcnt(0)
	v_readfirstlane_b32 s12, v4
	v_sub_u32_e32 v4, 0, v3
	v_rcp_iflag_f32_e32 v5, v5
	v_add_u32_e32 v6, s12, v0
	v_mul_f32_e32 v5, 0x4f7ffffe, v5
	v_cvt_u32_f32_e32 v5, v5
	v_mul_lo_u32 v0, v4, v5
	v_mul_hi_u32 v0, v5, v0
	v_add_u32_e32 v0, v5, v0
	v_mul_hi_u32 v0, v6, v0
	v_mul_lo_u32 v4, v0, v3
	v_sub_u32_e32 v4, v6, v4
	v_add_u32_e32 v5, 1, v0
	v_cmp_ge_u32_e32 vcc, v4, v3
	s_nop 1
	v_cndmask_b32_e32 v0, v0, v5, vcc
	v_sub_u32_e32 v5, v4, v3
	v_cndmask_b32_e32 v4, v4, v5, vcc
	v_add_u32_e32 v5, 1, v0
	v_cmp_ge_u32_e32 vcc, v4, v3
	v_add_u32_e32 v4, 1, v6
	s_nop 0
	v_cndmask_b32_e32 v0, v0, v5, vcc
	v_mul_lo_u32 v5, v3, v0
	v_add_u32_e32 v3, v5, v3
	v_cmp_ne_u32_e32 vcc, v4, v3
	s_and_saveexec_b64 s[12:13], vcc
	s_xor_b64 s[12:13], exec, s[12:13]
	s_cbranch_execz .LBB0_1208
	s_waitcnt lgkmcnt(0)
	v_readlane_b32 s18, v254, 18
	v_readlane_b32 s19, v254, 19
	s_nop 4
	global_load_dword v2, v1, s[18:19] sc1
	s_waitcnt vmcnt(0)
	v_cmp_eq_u32_e32 vcc, v2, v0
	s_and_saveexec_b64 s[16:17], vcc
	s_cbranch_execz .LBB0_1207
	s_mov_b32 s30, 1
	s_mov_b64 s[20:21], 0
	s_branch .LBB0_1198

; __device__ __forceinline__ unsigned xb_ld(unsigned* p)              { return __hip_atomic_load(p, __ATOMIC_RELAXED, __HIP_MEMORY_SCOPE_AGENT); }
; __device__ __forceinline__ unsigned xb_add(unsigned* p, unsigned v) { return __hip_atomic_fetch_add(p, v, __ATOMIC_RELAXED, __HIP_MEMORY_SCOPE_AGENT); }
; #define XB_SPIN(cond, bar) do { unsigned _sp = 0; while (cond) { __builtin_amdgcn_s_sleep(1); \
;     if ((++_sp & 255u) == 0u) { if (xb_ld(&(bar)[XB_TMO])) break; if (_sp > XB_SPIN_CAP) { atomicAdd(&(bar)[XB_TMO], 1u); break; } } } } while (0)
; __device__ __forceinline__ void xcd_barrier(const XcdBarrier& b) {
;     ...
;         const unsigned old = xb_add(&bar[XB_XSUB(b.x)], 1u);
;         const unsigned gen = old / nloc;
;         if (old + 1u == (gen + 1u) * nloc) {
;             __builtin_amdgcn_fence(__ATOMIC_RELEASE, "agent");
;             asm volatile("s_waitcnt vmcnt(0)" ::: "memory");
;             const unsigned og = xb_add(&bar[XB_TOP], 1u);
;             const unsigned tg = og / nx;
;             if (og + 1u == (tg + 1u) * nx) xb_add(&bar[XB_TOPGEN], 1u);
;             else XB_SPIN(xb_ld(&bar[XB_TOPGEN]) == tg, bar);
;             __builtin_amdgcn_fence(__ATOMIC_ACQUIRE, "agent");
;             xb_add(&bar[XB_XGEN(b.x)], 1u);
;             asm volatile("s_waitcnt vmcnt(0)" ::: "memory");
;         } else {
;             XB_SPIN(xb_ld(&bar[XB_XGEN(b.x)]) == gen, bar);
.LBB0_1297:
	s_or_b64 exec, exec, s[18:19]
	v_cvt_f32_u32_e32 v5, v3
	s_waitcnt vmcnt(0)
	v_readfirstlane_b32 s16, v4
	v_sub_u32_e32 v4, 0, v3
	v_rcp_iflag_f32_e32 v5, v5
	v_add_u32_e32 v6, s16, v0
	v_mul_f32_e32 v5, 0x4f7ffffe, v5
	v_cvt_u32_f32_e32 v5, v5
	v_mul_lo_u32 v0, v4, v5
	v_mul_hi_u32 v0, v5, v0
	v_add_u32_e32 v0, v5, v0
	v_mul_hi_u32 v0, v6, v0
	v_mul_lo_u32 v4, v0, v3
	v_sub_u32_e32 v4, v6, v4
	v_add_u32_e32 v5, 1, v0
	v_cmp_ge_u32_e32 vcc, v4, v3
	s_nop 1
	v_cndmask_b32_e32 v0, v0, v5, vcc
	v_sub_u32_e32 v5, v4, v3
	v_cndmask_b32_e32 v4, v4, v5, vcc
	v_add_u32_e32 v5, 1, v0
	v_cmp_ge_u32_e32 vcc, v4, v3
	v_add_u32_e32 v4, 1, v6
	s_nop 0
	v_cndmask_b32_e32 v0, v0, v5, vcc
	v_mul_lo_u32 v5, v3, v0
	v_add_u32_e32 v3, v5, v3
	v_cmp_ne_u32_e32 vcc, v4, v3
	s_and_saveexec_b64 s[16:17], vcc
	s_xor_b64 s[16:17], exec, s[16:17]
	s_cbranch_execz .LBB0_1311
	s_waitcnt lgkmcnt(0)
	v_readlane_b32 s20, v254, 18
	v_readlane_b32 s21, v254, 19
	s_nop 4
	global_load_dword v2, v1, s[20:21] sc1
	s_waitcnt vmcnt(0)
	v_cmp_eq_u32_e32 vcc, v2, v0
	s_and_saveexec_b64 s[18:19], vcc
	s_cbranch_execz .LBB0_1310
	s_mov_b32 s34, 1
	s_mov_b64 s[22:23], 0
	s_branch .LBB0_1301

; __device__ __forceinline__ unsigned xb_ld(unsigned* p)              { return __hip_atomic_load(p, __ATOMIC_RELAXED, __HIP_MEMORY_SCOPE_AGENT); }
; __device__ __forceinline__ unsigned xb_add(unsigned* p, unsigned v) { return __hip_atomic_fetch_add(p, v, __ATOMIC_RELAXED, __HIP_MEMORY_SCOPE_AGENT); }
; #define XB_SPIN(cond, bar) do { unsigned _sp = 0; while (cond) { __builtin_amdgcn_s_sleep(1); \
;     if ((++_sp & 255u) == 0u) { if (xb_ld(&(bar)[XB_TMO])) break; if (_sp > XB_SPIN_CAP) { atomicAdd(&(bar)[XB_TMO], 1u); break; } } } } while (0)
; __device__ __forceinline__ void xcd_barrier(const XcdBarrier& b) {
;     ...
;         const unsigned old = xb_add(&bar[XB_XSUB(b.x)], 1u);
;         const unsigned gen = old / nloc;
;         if (old + 1u == (gen + 1u) * nloc) {
;             __builtin_amdgcn_fence(__ATOMIC_RELEASE, "agent");
;             asm volatile("s_waitcnt vmcnt(0)" ::: "memory");
;             const unsigned og = xb_add(&bar[XB_TOP], 1u);
;             const unsigned tg = og / nx;
;             if (og + 1u == (tg + 1u) * nx) xb_add(&bar[XB_TOPGEN], 1u);
;             else XB_SPIN(xb_ld(&bar[XB_TOPGEN]) == tg, bar);
;             __builtin_amdgcn_fence(__ATOMIC_ACQUIRE, "agent");
;             xb_add(&bar[XB_XGEN(b.x)], 1u);
;             asm volatile("s_waitcnt vmcnt(0)" ::: "memory");
;         } else {
;             XB_SPIN(xb_ld(&bar[XB_XGEN(b.x)]) == gen, bar);
.LBB0_1365:
	s_or_b64 exec, exec, s[20:21]
	v_cvt_f32_u32_e32 v5, v3
	s_waitcnt vmcnt(0)
	v_readfirstlane_b32 s18, v4
	v_sub_u32_e32 v4, 0, v3
	v_rcp_iflag_f32_e32 v5, v5
	v_add_u32_e32 v6, s18, v0
	v_mul_f32_e32 v5, 0x4f7ffffe, v5
	v_cvt_u32_f32_e32 v5, v5
	v_mul_lo_u32 v0, v4, v5
	v_mul_hi_u32 v0, v5, v0
	v_add_u32_e32 v0, v5, v0
	v_mul_hi_u32 v0, v6, v0
	v_mul_lo_u32 v4, v0, v3
	v_sub_u32_e32 v4, v6, v4
	v_add_u32_e32 v5, 1, v0
	v_cmp_ge_u32_e32 vcc, v4, v3
	s_nop 1
	v_cndmask_b32_e32 v0, v0, v5, vcc
	v_sub_u32_e32 v5, v4, v3
	v_cndmask_b32_e32 v4, v4, v5, vcc
	v_add_u32_e32 v5, 1, v0
	v_cmp_ge_u32_e32 vcc, v4, v3
	v_add_u32_e32 v4, 1, v6
	s_nop 0
	v_cndmask_b32_e32 v0, v0, v5, vcc
	v_mul_lo_u32 v5, v3, v0
	v_add_u32_e32 v3, v5, v3
	v_cmp_ne_u32_e32 vcc, v4, v3
	s_and_saveexec_b64 s[18:19], vcc
	s_xor_b64 s[18:19], exec, s[18:19]
	s_cbranch_execz .LBB0_1379
	s_waitcnt lgkmcnt(0)
	v_readlane_b32 s22, v254, 18
	v_readlane_b32 s23, v254, 19
	s_nop 4
	global_load_dword v2, v1, s[22:23] sc1
	s_waitcnt vmcnt(0)
	v_cmp_eq_u32_e32 vcc, v2, v0
	s_and_saveexec_b64 s[20:21], vcc
	s_cbranch_execz .LBB0_1378
	s_mov_b32 s36, 1
	s_mov_b64 s[24:25], 0
	s_branch .LBB0_1369

; __device__ __forceinline__ unsigned xb_ld(unsigned* p)              { return __hip_atomic_load(p, __ATOMIC_RELAXED, __HIP_MEMORY_SCOPE_AGENT); }
; __device__ __forceinline__ unsigned xb_add(unsigned* p, unsigned v) { return __hip_atomic_fetch_add(p, v, __ATOMIC_RELAXED, __HIP_MEMORY_SCOPE_AGENT); }
; #define XB_SPIN(cond, bar) do { unsigned _sp = 0; while (cond) { __builtin_amdgcn_s_sleep(1); \
;     if ((++_sp & 255u) == 0u) { if (xb_ld(&(bar)[XB_TMO])) break; if (_sp > XB_SPIN_CAP) { atomicAdd(&(bar)[XB_TMO], 1u); break; } } } } while (0)
; __device__ __forceinline__ void xcd_barrier(const XcdBarrier& b) {
;     ...
;         const unsigned old = xb_add(&bar[XB_XSUB(b.x)], 1u);
;         const unsigned gen = old / nloc;
;         if (old + 1u == (gen + 1u) * nloc) {
;             __builtin_amdgcn_fence(__ATOMIC_RELEASE, "agent");
;             asm volatile("s_waitcnt vmcnt(0)" ::: "memory");
;             const unsigned og = xb_add(&bar[XB_TOP], 1u);
;             const unsigned tg = og / nx;
;             if (og + 1u == (tg + 1u) * nx) xb_add(&bar[XB_TOPGEN], 1u);
;             else XB_SPIN(xb_ld(&bar[XB_TOPGEN]) == tg, bar);
;             __builtin_amdgcn_fence(__ATOMIC_ACQUIRE, "agent");
;             xb_add(&bar[XB_XGEN(b.x)], 1u);
;             asm volatile("s_waitcnt vmcnt(0)" ::: "memory");
;         } else {
;             XB_SPIN(xb_ld(&bar[XB_XGEN(b.x)]) == gen, bar);
.LBB0_1736:
	s_or_b64 exec, exec, s[14:15]
	v_cvt_f32_u32_e32 v5, v3
	s_waitcnt vmcnt(0)
	v_readfirstlane_b32 s10, v4
	v_sub_u32_e32 v4, 0, v3
	v_rcp_iflag_f32_e32 v5, v5
	v_add_u32_e32 v6, s10, v0
	v_mul_f32_e32 v5, 0x4f7ffffe, v5
	v_cvt_u32_f32_e32 v5, v5
	v_mul_lo_u32 v0, v4, v5
	v_mul_hi_u32 v0, v5, v0
	v_add_u32_e32 v0, v5, v0
	v_mul_hi_u32 v0, v6, v0
	v_mul_lo_u32 v4, v0, v3
	v_sub_u32_e32 v4, v6, v4
	v_add_u32_e32 v5, 1, v0
	v_cmp_ge_u32_e32 vcc, v4, v3
	s_nop 1
	v_cndmask_b32_e32 v0, v0, v5, vcc
	v_sub_u32_e32 v5, v4, v3
	v_cndmask_b32_e32 v4, v4, v5, vcc
	v_add_u32_e32 v5, 1, v0
	v_cmp_ge_u32_e32 vcc, v4, v3
	v_add_u32_e32 v4, 1, v6
	s_nop 0
	v_cndmask_b32_e32 v0, v0, v5, vcc
	v_mul_lo_u32 v5, v3, v0
	v_add_u32_e32 v3, v5, v3
	v_cmp_ne_u32_e32 vcc, v4, v3
	s_and_saveexec_b64 s[10:11], vcc
	s_xor_b64 s[10:11], exec, s[10:11]
	s_cbranch_execz .LBB0_1750
	s_waitcnt lgkmcnt(0)
	v_readlane_b32 s16, v254, 18
	v_readlane_b32 s17, v254, 19
	s_nop 4
	global_load_dword v2, v1, s[16:17] sc1
	s_waitcnt vmcnt(0)
	v_cmp_eq_u32_e32 vcc, v2, v0
	s_and_saveexec_b64 s[14:15], vcc
	s_cbranch_execz .LBB0_1749
	s_mov_b32 s28, 1
	s_mov_b64 s[18:19], 0
	s_branch .LBB0_1740
